# grid barrier: non-leader workgroups wait on the cross-XCD generation word directly (one release hop less)
# baseline (speedup 1.0000x reference)
; __device__ __forceinline__ unsigned xb_ld(unsigned* p)              { return __hip_atomic_load(p, __ATOMIC_RELAXED, __HIP_MEMORY_SCOPE_AGENT); }
; __device__ __forceinline__ unsigned xb_add(unsigned* p, unsigned v) { return __hip_atomic_fetch_add(p, v, __ATOMIC_RELAXED, __HIP_MEMORY_SCOPE_AGENT); }
; #define XB_SPIN(cond, bar) do { unsigned _sp = 0; while (cond) { __builtin_amdgcn_s_sleep(1); \
;     if ((++_sp & 255u) == 0u) { if (xb_ld(&(bar)[XB_TMO])) break; if (_sp > XB_SPIN_CAP) { atomicAdd(&(bar)[XB_TMO], 1u); break; } } } } while (0)
; __device__ __forceinline__ void xcd_barrier(const XcdBarrier& b) {
;     ...
;         const unsigned old = xb_add(&bar[XB_XSUB(b.x)], 1u);
;         const unsigned gen = old / nloc;
;         if (old + 1u == (gen + 1u) * nloc) {
;             __builtin_amdgcn_fence(__ATOMIC_RELEASE, "agent");
;             asm volatile("s_waitcnt vmcnt(0)" ::: "memory");
;             const unsigned og = xb_add(&bar[XB_TOP], 1u);
;             const unsigned tg = og / nx;
;             if (og + 1u == (tg + 1u) * nx) xb_add(&bar[XB_TOPGEN], 1u);
;             else XB_SPIN(xb_ld(&bar[XB_TOPGEN]) == tg, bar);
;             __builtin_amdgcn_fence(__ATOMIC_ACQUIRE, "agent");
;             xb_add(&bar[XB_XGEN(b.x)], 1u);
;             asm volatile("s_waitcnt vmcnt(0)" ::: "memory");
;         } else {
;             XB_SPIN(xb_ld(&bar[XB_XGEN(b.x)]) == gen, bar);
;             __builtin_amdgcn_fence(__ATOMIC_ACQUIRE, "agent");
;             asm volatile("s_waitcnt vmcnt(0)" ::: "memory");
.LBB0_2981:
	s_or_b64 exec, exec, s[8:9]
	v_cvt_f32_u32_e32 v4, v2
	s_waitcnt vmcnt(0)
	v_readfirstlane_b32 s6, v3
	v_sub_u32_e32 v3, 0, v2
	v_rcp_iflag_f32_e32 v4, v4
	v_add_u32_e32 v5, s6, v1
	v_mul_f32_e32 v4, 0x4f7ffffe, v4
	v_cvt_u32_f32_e32 v4, v4
	v_mul_lo_u32 v1, v3, v4
	v_mul_hi_u32 v1, v4, v1
	v_add_u32_e32 v1, v4, v1
	v_mul_hi_u32 v1, v5, v1
	v_mul_lo_u32 v3, v1, v2
	v_sub_u32_e32 v3, v5, v3
	v_add_u32_e32 v4, 1, v1
	v_cmp_ge_u32_e32 vcc, v3, v2
	s_nop 1
	v_cndmask_b32_e32 v1, v1, v4, vcc
	v_sub_u32_e32 v4, v3, v2
	v_cndmask_b32_e32 v3, v3, v4, vcc
	v_add_u32_e32 v4, 1, v1
	v_cmp_ge_u32_e32 vcc, v3, v2
	v_add_u32_e32 v3, 1, v5
	s_nop 0
	v_cndmask_b32_e32 v1, v1, v4, vcc
	v_mul_lo_u32 v4, v2, v1
	v_add_u32_e32 v2, v4, v2
	v_cmp_ne_u32_e32 vcc, v3, v2
	s_and_saveexec_b64 s[6:7], vcc
	s_xor_b64 s[6:7], exec, s[6:7]
	s_cbranch_execz .LBB0_2995
	s_waitcnt lgkmcnt(0)
	v_readlane_b32 s10, v253, 55
	v_readlane_b32 s11, v253, 56
	s_nop 4
	global_load_dword v0, v215, s[10:11] sc1
	s_waitcnt vmcnt(0)
	v_cmp_eq_u32_e32 vcc, v0, v1
	s_and_saveexec_b64 s[8:9], vcc
	s_cbranch_execz .LBB0_2994
	s_mov_b32 s22, 1
	s_mov_b64 s[12:13], 0
	s_branch .LBB0_2985
